# phase F gate tiles requested at the top of every two-K-tile step (cache warm-up in non-closing steps, operands in the closing step); counted waits shifted so the next A/B tile loads are no longer drai
# baseline (speedup 1.0000x reference)
; #define FG_BAR() do { asm volatile("s_waitcnt lgkmcnt(0)" ::: "memory"); __builtin_amdgcn_s_barrier(); asm volatile("" ::: "memory"); } while (0)
; __device__ __forceinline__ void branch_tile(LAS unsigned char* lds, const bf16_t* omix, const bf16_t* wbr, const bf16_t* brg, bf16_t* mix, int pm, int pn, int tid) {
;     ...
;     for (int kt = 0; kt < 16; kt += 2) {
;         fg_ld(A, Bt, (kt + 2 < 16 ? kt + 2 : 15), tid, ra0, rb0);
;         FG_COMPUTE(0);
;         fg_st(lds + FG_STAGE, tid, ra1, rb1);
;         FG_BAR();
;         fg_ld(A, Bt, (kt + 3 < 16 ? kt + 3 : 15), tid, ra1, rb1);
;         const bool segend = (kt == 2) || (kt == 6) || (kt == 14);
;         const int s = kt == 2 ? 0 : (kt == 6 ? 1 : 2);
;         u32x4 g0, g1;
;     ...
;         if (segend) { FG_GLD(g0, 0, 0); FG_GLD(g1, 0, 1); }
;         FG_COMPUTE(1);
;         if (segend) {
;             FG_GATE(g0, 0, 0); FG_GLD(g0, 1, 0); FG_ACC(0, 0);
;             FG_GATE(g1, 0, 1); FG_GLD(g1, 1, 1); FG_ACC(0, 1);
;             FG_GATE(g0, 1, 0); FG_ACC(1, 0);
;             FG_GATE(g1, 1, 1); FG_ACC(1, 1);
.LBB0_1091:
	s_waitcnt vmcnt(15)
	ds_write_b128 v219, v[98:101]
	s_waitcnt vmcnt(14)
	ds_write_b128 v221, v[102:105]
	s_waitcnt vmcnt(13)
	ds_write_b128 v223, v[106:109]
	s_waitcnt vmcnt(12)
	ds_write_b128 v225, v[110:113]
	s_waitcnt vmcnt(11)
	ds_write_b128 v219, v[114:117] offset:36864
	s_waitcnt vmcnt(10)
	ds_write_b128 v221, v[118:121] offset:36864
	s_waitcnt lgkmcnt(0)
	s_barrier
	s_andn2_b64 vcc, exec, s[14:15]
	s_addk_i32 s26, 0x80
	s_cbranch_vccz .LBB0_1089
.LBB0_1092:
	s_mov_b32 s4, s27
	s_add_i32 s27, s27, 2
	s_cmp_gt_u32 s27, 13
	s_cselect_b64 s[14:15], -1, 0
	s_cmp_lt_u32 s27, 14
	s_cselect_b32 s76, s26, 0x3c0
	s_lshl_b64 s[28:29], s[76:77], 1
	s_add_u32 s30, s10, s28
	s_addc_u32 s31, s11, s29
	s_add_u32 s28, s12, s28
	s_addc_u32 s29, s13, s29
	v_lshl_add_u64 v[98:99], s[30:31], 0, v[130:131]
	v_lshl_add_u64 v[102:103], s[30:31], 0, v[132:133]
	v_lshl_add_u64 v[106:107], s[30:31], 0, v[134:135]
	v_lshl_add_u64 v[110:111], s[30:31], 0, v[136:137]
	v_lshl_add_u64 v[114:115], s[28:29], 0, v[130:131]
	v_lshl_add_u64 v[118:119], s[28:29], 0, v[132:133]
	global_load_dwordx4 v[98:101], v[98:99], off
	s_min_u32 s5, s27, 12
	global_load_dwordx4 v[102:105], v[102:103], off
	s_lshl_b32 s5, s5, 7
	global_load_dwordx4 v[106:109], v[106:107], off
	s_add_u32 s28, s10, s5
	global_load_dwordx4 v[110:113], v[110:111], off
	s_addc_u32 s29, s11, 0
	global_load_dwordx4 v[114:117], v[114:115], off
	s_nop 0
	global_load_dwordx4 v[118:121], v[118:119], off
	s_cmp_gt_u32 s27, 2
	s_cselect_b32 s98, 0x400, 0
	s_cmp_gt_u32 s27, 6
	s_cselect_b32 s98, 0x800, s98
	v_or_b32_e32 v180, s98, v231
	v_add_u32_e32 v90, v180, v229
	v_or_b32_e32 v94, 32, v229
	v_add_u32_e32 v94, v94, v180
	v_add_u32_e32 v184, 0x18000, v94
	v_add_u32_e32 v180, 0x18000, v90
	global_load_dwordx4 v[90:93], v90, s[6:7]
	s_nop 0
	global_load_dwordx4 v[94:97], v94, s[6:7]
	s_nop 0
	global_load_dwordx4 v[180:183], v180, s[6:7]
	s_nop 0
	global_load_dwordx4 v[184:187], v184, s[6:7]
	ds_read_b128 v[122:125], v242 offset:4608
	ds_read_b128 v[126:129], v238 offset:41472
	ds_read_b128 v[170:173], v242
	ds_read_b128 v[174:177], v242 offset:32
	ds_read_b128 v[244:247], v238 offset:36864
	ds_read_b128 v[248:251], v238 offset:36896
	s_waitcnt lgkmcnt(1)
	v_mfma_f32_32x32x16_bf16 v[48:63], v[170:173], v[244:247], v[48:63]
	v_mfma_f32_32x32x16_bf16 v[32:47], v[170:173], v[126:129], v[32:47]
	v_mfma_f32_32x32x16_bf16 v[16:31], v[122:125], v[244:247], v[16:31]
	v_mfma_f32_32x32x16_bf16 v[0:15], v[122:125], v[126:129], v[0:15]
	ds_read_b128 v[122:125], v242 offset:4640
	ds_read_b128 v[126:129], v238 offset:41504
	s_waitcnt lgkmcnt(2)
	v_mfma_f32_32x32x16_bf16 v[48:63], v[174:177], v[248:251], v[48:63]
	s_waitcnt lgkmcnt(0)
	v_mfma_f32_32x32x16_bf16 v[32:47], v[174:177], v[126:129], v[32:47]
	v_mfma_f32_32x32x16_bf16 v[16:31], v[122:125], v[248:251], v[16:31]
	v_mfma_f32_32x32x16_bf16 v[0:15], v[122:125], v[126:129], v[0:15]
	ds_read_b128 v[122:125], v242 offset:64
	ds_read_b128 v[126:129], v242 offset:4672
	ds_read_b128 v[170:173], v238 offset:36928
	ds_read_b128 v[174:177], v238 offset:41536
	s_waitcnt lgkmcnt(1)
	v_mfma_f32_32x32x16_bf16 v[48:63], v[122:125], v[170:173], v[48:63]
	s_waitcnt lgkmcnt(0)
	v_mfma_f32_32x32x16_bf16 v[32:47], v[122:125], v[174:177], v[32:47]
	v_mfma_f32_32x32x16_bf16 v[16:31], v[126:129], v[170:173], v[16:31]
	v_mfma_f32_32x32x16_bf16 v[0:15], v[126:129], v[174:177], v[0:15]
	ds_read_b128 v[122:125], v242 offset:96
	ds_read_b128 v[126:129], v242 offset:4704
	ds_read_b128 v[170:173], v238 offset:36960
	ds_read_b128 v[174:177], v238 offset:41568
	s_waitcnt vmcnt(15)
	ds_write_b128 v219, v[64:67] offset:55296
	s_waitcnt vmcnt(11)
	ds_write_b128 v221, v[72:75] offset:55296
	ds_write_b128 v223, v[68:71] offset:55296
	ds_write_b128 v225, v[76:79] offset:55296
	v_add_u32_e32 v64, v216, v213
	ds_write_b128 v64, v[82:85]
	v_add_u32_e32 v64, v216, v215
	s_waitcnt vmcnt(10)
	ds_write_b128 v64, v[86:89]
	s_waitcnt lgkmcnt(0)
	s_barrier
	v_lshl_add_u64 v[64:65], s[28:29], 0, v[130:131]
	v_lshl_add_u64 v[68:69], s[28:29], 0, v[132:133]
	global_load_dwordx4 v[64:67], v[64:65], off offset:384
	v_lshl_add_u64 v[76:77], s[28:29], 0, v[136:137]
	global_load_dwordx4 v[72:75], v[68:69], off offset:384
	v_lshl_add_u64 v[68:69], s[28:29], 0, v[134:135]
	s_add_u32 s28, s12, s5
	s_addc_u32 s29, s13, 0
	v_lshl_add_u64 v[82:83], s[28:29], 0, v[130:131]
	v_lshl_add_u64 v[86:87], s[28:29], 0, v[132:133]
	global_load_dwordx4 v[68:71], v[68:69], off offset:384
	s_cmp_lt_u32 s27, 15
	global_load_dwordx4 v[76:79], v[76:77], off offset:384
	s_waitcnt lgkmcnt(7)
	v_mfma_f32_32x32x16_bf16 v[48:63], v[122:125], v[170:173], v[48:63]
	global_load_dwordx4 v[82:85], v[82:83], off offset:384
	s_cselect_b64 s[28:29], -1, 0
	global_load_dwordx4 v[86:89], v[86:87], off offset:384
	s_lshr_b32 s5, 0x4044, s27
	s_bitcmp1_b32 s5, 0
	s_cselect_b64 s[30:31], -1, 0
	s_and_b64 s[28:29], s[28:29], s[30:31]
	s_waitcnt lgkmcnt(6)
	v_mfma_f32_32x32x16_bf16 v[32:47], v[122:125], v[174:177], v[32:47]
	s_cmp_eq_u32 s4, 4
	s_movk_i32 s5, 0x800
	s_cselect_b32 s5, 0x400, s5
	s_cmp_lg_u32 s4, 0
	s_cselect_b32 s30, s5, 0
	v_cndmask_b32_e64 v122, 0, 1, s[28:29]
	v_cmp_ne_u32_e64 s[4:5], 1, v122
	v_mfma_f32_32x32x16_bf16 v[16:31], v[126:129], v[170:173], v[16:31]
	s_andn2_b64 vcc, exec, s[28:29]
	v_or_b32_e32 v122, s30, v231
	v_mfma_f32_32x32x16_bf16 v[0:15], v[126:129], v[174:177], v[0:15]
	s_cbranch_vccnz .LBB0_1094
; __device__ __forceinline__ void branch_tile(LAS unsigned char* lds, const bf16_t* omix, const bf16_t* wbr, const bf16_t* brg, bf16_t* mix, int pm, int pn, int tid) {
;     ...
;         FG_COMPUTE(1);
;         if (segend) {
;             FG_GATE(g0, 0, 0); FG_GLD(g0, 1, 0); FG_ACC(0, 0);
;             FG_GATE(g1, 0, 1); FG_GLD(g1, 1, 1); FG_ACC(0, 1);
;             FG_GATE(g0, 1, 0); FG_ACC(1, 0);
;             FG_GATE(g1, 1, 1); FG_ACC(1, 1);
.LBB0_1094:
	ds_read_b128 v[124:127], v242 offset:55296
	ds_read_b128 v[170:173], v239
	ds_read_b128 v[174:177], v239 offset:4608
	s_and_b64 vcc, exec, s[4:5]
	s_waitcnt lgkmcnt(1)
	v_mfma_f32_32x32x16_bf16 v[48:63], v[124:127], v[170:173], v[48:63]
	s_waitcnt lgkmcnt(0)
	v_mfma_f32_32x32x16_bf16 v[32:47], v[124:127], v[174:177], v[32:47]
	ds_read_b128 v[124:127], v242 offset:59904
	s_waitcnt lgkmcnt(0)
	v_mfma_f32_32x32x16_bf16 v[16:31], v[124:127], v[170:173], v[16:31]
	v_mfma_f32_32x32x16_bf16 v[0:15], v[124:127], v[174:177], v[0:15]
	ds_read_b128 v[124:127], v242 offset:55328
	ds_read_b128 v[170:173], v239 offset:32
	ds_read_b128 v[174:177], v239 offset:4640
	s_waitcnt lgkmcnt(1)
	v_mfma_f32_32x32x16_bf16 v[48:63], v[124:127], v[170:173], v[48:63]
	s_waitcnt lgkmcnt(0)
	v_mfma_f32_32x32x16_bf16 v[32:47], v[124:127], v[174:177], v[32:47]
	ds_read_b128 v[124:127], v242 offset:59936
	s_waitcnt lgkmcnt(0)
	v_mfma_f32_32x32x16_bf16 v[16:31], v[124:127], v[170:173], v[16:31]
	v_mfma_f32_32x32x16_bf16 v[0:15], v[124:127], v[174:177], v[0:15]
	ds_read_b128 v[124:127], v242 offset:55360
	ds_read_b128 v[170:173], v239 offset:64
	ds_read_b128 v[174:177], v239 offset:4672
	s_waitcnt lgkmcnt(1)
	v_mfma_f32_32x32x16_bf16 v[48:63], v[124:127], v[170:173], v[48:63]
	s_waitcnt lgkmcnt(0)
	v_mfma_f32_32x32x16_bf16 v[32:47], v[124:127], v[174:177], v[32:47]
	ds_read_b128 v[124:127], v242 offset:59968
	s_waitcnt lgkmcnt(0)
	v_mfma_f32_32x32x16_bf16 v[16:31], v[124:127], v[170:173], v[16:31]
	v_mfma_f32_32x32x16_bf16 v[0:15], v[124:127], v[174:177], v[0:15]
	ds_read_b128 v[124:127], v242 offset:55392
	ds_read_b128 v[170:173], v239 offset:96
	ds_read_b128 v[174:177], v239 offset:4704
	s_waitcnt lgkmcnt(1)
	v_mfma_f32_32x32x16_bf16 v[48:63], v[124:127], v[170:173], v[48:63]
	s_waitcnt lgkmcnt(0)
	v_mfma_f32_32x32x16_bf16 v[32:47], v[124:127], v[174:177], v[32:47]
	ds_read_b128 v[124:127], v242 offset:60000
	s_waitcnt lgkmcnt(0)
	v_mfma_f32_32x32x16_bf16 v[16:31], v[124:127], v[170:173], v[16:31]
	v_mfma_f32_32x32x16_bf16 v[0:15], v[124:127], v[174:177], v[0:15]
	s_cbranch_vccnz .LBB0_1091
	s_waitcnt vmcnt(9)
	ds_write_b128 v240, v[90:93]
	ds_read_u8 v123, v241
	ds_read_u8 v124, v241 offset:48
	ds_read_u8 v125, v241 offset:96
	ds_read_u8 v126, v241 offset:144
	ds_read_u8 v127, v241 offset:384
	ds_read_u8 v128, v241 offset:432
	ds_read_u8 v129, v241 offset:480
	ds_read_u8 v170, v241 offset:528
	s_waitcnt lgkmcnt(7)
	v_cvt_f32_ubyte0_e32 v123, v123
	v_mul_f32_e32 v123, 0x3b808081, v123
	s_waitcnt lgkmcnt(6)
	v_cvt_f32_ubyte0_e32 v124, v124
	v_lshlrev_b32_e32 v179, 16, v230
	v_mul_f32_e32 v124, 0x3b808081, v124
	v_fmac_f32_e32 v179, v123, v48
	v_and_b32_e32 v48, 0xffff0000, v230
	s_waitcnt lgkmcnt(5)
	v_cvt_f32_ubyte0_e32 v125, v125
	s_waitcnt lgkmcnt(4)
	v_cvt_f32_ubyte0_e32 v126, v126
	v_fmac_f32_e32 v48, v124, v49
	v_mul_f32_e32 v125, 0x3b808081, v125
	v_mul_f32_e32 v126, 0x3b808081, v126
	v_cvt_pk_bf16_f32 v230, v179, v48
	v_lshlrev_b32_e32 v48, 16, v237
	v_and_b32_e32 v49, 0xffff0000, v237
	s_waitcnt lgkmcnt(3)
	v_cvt_f32_ubyte0_e32 v127, v127
	s_waitcnt lgkmcnt(2)
	v_cvt_f32_ubyte0_e32 v128, v128
	v_fmac_f32_e32 v48, v125, v50
	v_fmac_f32_e32 v49, v126, v51
	v_mul_f32_e32 v127, 0x3b808081, v127
	v_mul_f32_e32 v128, 0x3b808081, v128
	v_cvt_pk_bf16_f32 v237, v48, v49
	v_lshlrev_b32_e32 v48, 16, v236
	v_and_b32_e32 v49, 0xffff0000, v236
	s_waitcnt lgkmcnt(1)
	v_cvt_f32_ubyte0_e32 v129, v129
	s_waitcnt lgkmcnt(0)
	v_cvt_f32_ubyte0_e32 v170, v170
	v_fmac_f32_e32 v48, v127, v52
	v_fmac_f32_e32 v49, v128, v53
	v_mul_f32_e32 v129, 0x3b808081, v129
	v_mul_f32_e32 v170, 0x3b808081, v170
	ds_read_u8 v171, v241 offset:768
	ds_read_u8 v172, v241 offset:816
	ds_read_u8 v173, v241 offset:864
	ds_read_u8 v174, v241 offset:912
	ds_read_u8 v175, v241 offset:1152
	ds_read_u8 v176, v241 offset:1200
	ds_read_u8 v177, v241 offset:1248
	ds_read_u8 v178, v241 offset:1296
	v_cvt_pk_bf16_f32 v236, v48, v49
	v_lshlrev_b32_e32 v48, 16, v235
	v_and_b32_e32 v49, 0xffff0000, v235
	s_waitcnt lgkmcnt(7)
	v_cvt_f32_ubyte0_e32 v171, v171
	s_waitcnt lgkmcnt(6)
	v_cvt_f32_ubyte0_e32 v172, v172
	v_fmac_f32_e32 v48, v129, v54
	v_fmac_f32_e32 v49, v170, v55
	v_mul_f32_e32 v171, 0x3b808081, v171
	v_mul_f32_e32 v172, 0x3b808081, v172
	v_cvt_pk_bf16_f32 v235, v48, v49
	v_lshlrev_b32_e32 v48, 16, v234
	v_and_b32_e32 v49, 0xffff0000, v234
	s_waitcnt lgkmcnt(5)
	v_cvt_f32_ubyte0_e32 v173, v173
	s_waitcnt lgkmcnt(4)
	v_cvt_f32_ubyte0_e32 v174, v174
	v_fmac_f32_e32 v48, v171, v56
	v_fmac_f32_e32 v49, v172, v57
	v_mul_f32_e32 v173, 0x3b808081, v173
	v_mul_f32_e32 v174, 0x3b808081, v174
	v_cvt_pk_bf16_f32 v234, v48, v49
	v_lshlrev_b32_e32 v48, 16, v233
	v_and_b32_e32 v49, 0xffff0000, v233
	s_waitcnt lgkmcnt(3)
	v_cvt_f32_ubyte0_e32 v175, v175
	s_waitcnt lgkmcnt(2)
	v_cvt_f32_ubyte0_e32 v176, v176
	v_fmac_f32_e32 v48, v173, v58
	v_fmac_f32_e32 v49, v174, v59
	v_mul_f32_e32 v175, 0x3b808081, v175
	v_mul_f32_e32 v176, 0x3b808081, v176
	v_cvt_pk_bf16_f32 v233, v48, v49
	v_lshlrev_b32_e32 v48, 16, v232
	v_and_b32_e32 v49, 0xffff0000, v232
	s_waitcnt lgkmcnt(1)
	v_cvt_f32_ubyte0_e32 v177, v177
	s_waitcnt lgkmcnt(0)
	v_cvt_f32_ubyte0_e32 v178, v178
	v_fmac_f32_e32 v48, v175, v60
	v_fmac_f32_e32 v49, v176, v61
	v_mul_f32_e32 v177, 0x3b808081, v177
	v_mul_f32_e32 v178, 0x3b808081, v178
	v_cvt_pk_bf16_f32 v232, v48, v49
	v_lshlrev_b32_e32 v48, 16, v80
	v_and_b32_e32 v49, 0xffff0000, v80
	v_fmac_f32_e32 v48, v177, v62
	v_fmac_f32_e32 v49, v178, v63
	v_cvt_pk_bf16_f32 v80, v48, v49
	s_waitcnt vmcnt(8)
; __device__ __forceinline__ void branch_tile(LAS unsigned char* lds, const bf16_t* omix, const bf16_t* wbr, const bf16_t* brg, bf16_t* mix, int pm, int pn, int tid) {
;     ...
;         if (segend) { FG_GLD(g0, 0, 0); FG_GLD(g1, 0, 1); }
;         FG_COMPUTE(1);
;         if (segend) {
;             FG_GATE(g0, 0, 0); FG_GLD(g0, 1, 0); FG_ACC(0, 0);
;             FG_GATE(g1, 0, 1); FG_GLD(g1, 1, 1); FG_ACC(0, 1);
;             FG_GATE(g0, 1, 0); FG_ACC(1, 0);
;             FG_GATE(g1, 1, 1); FG_ACC(1, 1);
	ds_write_b128 v240, v[94:97]
	ds_read_u8 v48, v241
	ds_read_u8 v49, v241 offset:48
	ds_read_u8 v50, v241 offset:96
	ds_read_u8 v51, v241 offset:144
	ds_read_u8 v52, v241 offset:384
	ds_read_u8 v53, v241 offset:432
	ds_read_u8 v54, v241 offset:480
	ds_read_u8 v55, v241 offset:528
	s_waitcnt lgkmcnt(7)
	v_cvt_f32_ubyte0_e32 v48, v48
	v_mul_f32_e32 v48, 0x3b808081, v48
	s_waitcnt lgkmcnt(6)
	v_cvt_f32_ubyte0_e32 v49, v49
	v_lshlrev_b32_e32 v122, 16, v228
	v_mul_f32_e32 v49, 0x3b808081, v49
	v_fmac_f32_e32 v122, v48, v32
	v_and_b32_e32 v32, 0xffff0000, v228
	s_waitcnt lgkmcnt(5)
	v_cvt_f32_ubyte0_e32 v50, v50
	s_waitcnt lgkmcnt(4)
	v_cvt_f32_ubyte0_e32 v51, v51
	v_fmac_f32_e32 v32, v49, v33
	v_mul_f32_e32 v50, 0x3b808081, v50
	v_mul_f32_e32 v51, 0x3b808081, v51
	v_cvt_pk_bf16_f32 v228, v122, v32
	v_lshlrev_b32_e32 v32, 16, v227
	v_and_b32_e32 v33, 0xffff0000, v227
	s_waitcnt lgkmcnt(3)
	v_cvt_f32_ubyte0_e32 v52, v52
	s_waitcnt lgkmcnt(2)
	v_cvt_f32_ubyte0_e32 v53, v53
	v_fmac_f32_e32 v32, v50, v34
	v_fmac_f32_e32 v33, v51, v35
	v_mul_f32_e32 v52, 0x3b808081, v52
	v_mul_f32_e32 v53, 0x3b808081, v53
	v_cvt_pk_bf16_f32 v227, v32, v33
	v_lshlrev_b32_e32 v32, 16, v226
	v_and_b32_e32 v33, 0xffff0000, v226
	s_waitcnt lgkmcnt(1)
	v_cvt_f32_ubyte0_e32 v54, v54
	s_waitcnt lgkmcnt(0)
	v_cvt_f32_ubyte0_e32 v55, v55
	v_fmac_f32_e32 v32, v52, v36
	v_fmac_f32_e32 v33, v53, v37
	v_mul_f32_e32 v54, 0x3b808081, v54
	v_mul_f32_e32 v55, 0x3b808081, v55
	ds_read_u8 v56, v241 offset:768
	ds_read_u8 v57, v241 offset:816
	ds_read_u8 v58, v241 offset:864
	ds_read_u8 v59, v241 offset:912
	ds_read_u8 v60, v241 offset:1152
	ds_read_u8 v61, v241 offset:1200
	ds_read_u8 v62, v241 offset:1248
	ds_read_u8 v63, v241 offset:1296
	v_cvt_pk_bf16_f32 v226, v32, v33
	v_lshlrev_b32_e32 v32, 16, v224
	v_and_b32_e32 v33, 0xffff0000, v224
	s_waitcnt lgkmcnt(7)
	v_cvt_f32_ubyte0_e32 v56, v56
	s_waitcnt lgkmcnt(6)
	v_cvt_f32_ubyte0_e32 v57, v57
	v_fmac_f32_e32 v32, v54, v38
	v_fmac_f32_e32 v33, v55, v39
	v_mul_f32_e32 v56, 0x3b808081, v56
	v_mul_f32_e32 v57, 0x3b808081, v57
	v_cvt_pk_bf16_f32 v224, v32, v33
	v_lshlrev_b32_e32 v32, 16, v222
	v_and_b32_e32 v33, 0xffff0000, v222
	s_waitcnt lgkmcnt(5)
	v_cvt_f32_ubyte0_e32 v58, v58
	s_waitcnt lgkmcnt(4)
	v_cvt_f32_ubyte0_e32 v59, v59
	v_fmac_f32_e32 v32, v56, v40
	v_fmac_f32_e32 v33, v57, v41
	v_mul_f32_e32 v58, 0x3b808081, v58
	v_mul_f32_e32 v59, 0x3b808081, v59
	v_cvt_pk_bf16_f32 v222, v32, v33
	v_lshlrev_b32_e32 v32, 16, v220
	v_and_b32_e32 v33, 0xffff0000, v220
	s_waitcnt lgkmcnt(3)
	v_cvt_f32_ubyte0_e32 v60, v60
	s_waitcnt lgkmcnt(2)
	v_cvt_f32_ubyte0_e32 v61, v61
	v_fmac_f32_e32 v32, v58, v42
	v_fmac_f32_e32 v33, v59, v43
	v_mul_f32_e32 v60, 0x3b808081, v60
	v_mul_f32_e32 v61, 0x3b808081, v61
	v_cvt_pk_bf16_f32 v220, v32, v33
	v_lshlrev_b32_e32 v32, 16, v218
	v_and_b32_e32 v33, 0xffff0000, v218
	s_waitcnt lgkmcnt(1)
	v_cvt_f32_ubyte0_e32 v62, v62
	s_waitcnt lgkmcnt(0)
	v_cvt_f32_ubyte0_e32 v63, v63
	v_fmac_f32_e32 v32, v60, v44
	v_fmac_f32_e32 v33, v61, v45
	v_mul_f32_e32 v62, 0x3b808081, v62
	v_mul_f32_e32 v63, 0x3b808081, v63
	v_cvt_pk_bf16_f32 v218, v32, v33
	v_lshlrev_b32_e32 v32, 16, v217
	v_and_b32_e32 v33, 0xffff0000, v217
	v_fmac_f32_e32 v32, v62, v46
	v_fmac_f32_e32 v33, v63, v47
	s_waitcnt vmcnt(7)
	ds_write_b128 v240, v[180:183]
	v_cvt_pk_bf16_f32 v217, v32, v33
	ds_read_u8 v32, v241
	ds_read_u8 v33, v241 offset:48
	ds_read_u8 v34, v241 offset:96
	ds_read_u8 v35, v241 offset:144
	ds_read_u8 v36, v241 offset:384
	ds_read_u8 v37, v241 offset:432
	ds_read_u8 v38, v241 offset:480
	ds_read_u8 v39, v241 offset:528
	s_waitcnt lgkmcnt(7)
	v_cvt_f32_ubyte0_e32 v32, v32
	v_mul_f32_e32 v32, 0x3b808081, v32
	s_waitcnt lgkmcnt(6)
	v_cvt_f32_ubyte0_e32 v33, v33
	v_lshlrev_b32_e32 v48, 16, v210
	v_mul_f32_e32 v33, 0x3b808081, v33
	v_fmac_f32_e32 v48, v32, v16
	v_and_b32_e32 v16, 0xffff0000, v210
	s_waitcnt lgkmcnt(5)
	v_cvt_f32_ubyte0_e32 v34, v34
	s_waitcnt lgkmcnt(4)
	v_cvt_f32_ubyte0_e32 v35, v35
	v_fmac_f32_e32 v16, v33, v17
	v_mul_f32_e32 v34, 0x3b808081, v34
	v_mul_f32_e32 v35, 0x3b808081, v35
	v_cvt_pk_bf16_f32 v210, v48, v16
	v_lshlrev_b32_e32 v16, 16, v163
	v_and_b32_e32 v17, 0xffff0000, v163
	s_waitcnt lgkmcnt(3)
	v_cvt_f32_ubyte0_e32 v36, v36
	s_waitcnt lgkmcnt(2)
	v_cvt_f32_ubyte0_e32 v37, v37
	v_fmac_f32_e32 v16, v34, v18
	v_fmac_f32_e32 v17, v35, v19
	v_mul_f32_e32 v36, 0x3b808081, v36
	v_mul_f32_e32 v37, 0x3b808081, v37
	v_cvt_pk_bf16_f32 v163, v16, v17
	v_lshlrev_b32_e32 v16, 16, v162
	v_and_b32_e32 v17, 0xffff0000, v162
	s_waitcnt lgkmcnt(1)
	v_cvt_f32_ubyte0_e32 v38, v38
	s_waitcnt lgkmcnt(0)
	v_cvt_f32_ubyte0_e32 v39, v39
	v_fmac_f32_e32 v16, v36, v20
	v_fmac_f32_e32 v17, v37, v21
	v_mul_f32_e32 v38, 0x3b808081, v38
	v_mul_f32_e32 v39, 0x3b808081, v39
	ds_read_u8 v40, v241 offset:768
	ds_read_u8 v41, v241 offset:816
	ds_read_u8 v42, v241 offset:864
	ds_read_u8 v43, v241 offset:912
	ds_read_u8 v44, v241 offset:1152
	ds_read_u8 v45, v241 offset:1200
	ds_read_u8 v46, v241 offset:1248
	ds_read_u8 v47, v241 offset:1296
	v_cvt_pk_bf16_f32 v162, v16, v17
	v_lshlrev_b32_e32 v16, 16, v160
	v_and_b32_e32 v17, 0xffff0000, v160
	s_waitcnt lgkmcnt(7)
	v_cvt_f32_ubyte0_e32 v40, v40
	s_waitcnt lgkmcnt(6)
	v_cvt_f32_ubyte0_e32 v41, v41
	v_fmac_f32_e32 v16, v38, v22
	v_fmac_f32_e32 v17, v39, v23
	v_mul_f32_e32 v40, 0x3b808081, v40
	v_mul_f32_e32 v41, 0x3b808081, v41
	v_cvt_pk_bf16_f32 v160, v16, v17
	v_lshlrev_b32_e32 v16, 16, v158
	v_and_b32_e32 v17, 0xffff0000, v158
	s_waitcnt lgkmcnt(5)
	v_cvt_f32_ubyte0_e32 v42, v42
	s_waitcnt lgkmcnt(4)
; #define FG_BAR() do { asm volatile("s_waitcnt lgkmcnt(0)" ::: "memory"); __builtin_amdgcn_s_barrier(); asm volatile("" ::: "memory"); } while (0)
; __device__ __forceinline__ void branch_tile(LAS unsigned char* lds, const bf16_t* omix, const bf16_t* wbr, const bf16_t* brg, bf16_t* mix, int pm, int pn, int tid) {
;     ...
;         if (segend) { FG_GLD(g0, 0, 0); FG_GLD(g1, 0, 1); }
;         FG_COMPUTE(1);
;         if (segend) {
;             FG_GATE(g0, 0, 0); FG_GLD(g0, 1, 0); FG_ACC(0, 0);
;             FG_GATE(g1, 0, 1); FG_GLD(g1, 1, 1); FG_ACC(0, 1);
;             FG_GATE(g0, 1, 0); FG_ACC(1, 0);
;             FG_GATE(g1, 1, 1); FG_ACC(1, 1);
;         }
;     ...
;         fg_st(lds, tid, ra0, rb0);
;         FG_BAR();
;     }
	v_cvt_f32_ubyte0_e32 v43, v43
	v_fmac_f32_e32 v16, v40, v24
	v_fmac_f32_e32 v17, v41, v25
	v_mul_f32_e32 v42, 0x3b808081, v42
	v_mul_f32_e32 v43, 0x3b808081, v43
	v_cvt_pk_bf16_f32 v158, v16, v17
	v_lshlrev_b32_e32 v16, 16, v157
	v_and_b32_e32 v17, 0xffff0000, v157
	s_waitcnt lgkmcnt(3)
	v_cvt_f32_ubyte0_e32 v44, v44
	s_waitcnt lgkmcnt(2)
	v_cvt_f32_ubyte0_e32 v45, v45
	v_fmac_f32_e32 v16, v42, v26
	v_fmac_f32_e32 v17, v43, v27
	v_mul_f32_e32 v44, 0x3b808081, v44
	v_mul_f32_e32 v45, 0x3b808081, v45
	v_cvt_pk_bf16_f32 v157, v16, v17
	v_lshlrev_b32_e32 v16, 16, v156
	v_and_b32_e32 v17, 0xffff0000, v156
	s_waitcnt lgkmcnt(1)
	v_cvt_f32_ubyte0_e32 v46, v46
	s_waitcnt lgkmcnt(0)
	v_cvt_f32_ubyte0_e32 v47, v47
	v_fmac_f32_e32 v16, v44, v28
	v_fmac_f32_e32 v17, v45, v29
	v_mul_f32_e32 v46, 0x3b808081, v46
	v_mul_f32_e32 v47, 0x3b808081, v47
	v_cvt_pk_bf16_f32 v156, v16, v17
	v_lshlrev_b32_e32 v16, 16, v155
	v_and_b32_e32 v17, 0xffff0000, v155
	v_fmac_f32_e32 v16, v46, v30
	v_fmac_f32_e32 v17, v47, v31
	s_waitcnt vmcnt(6)
	ds_write_b128 v240, v[184:187]
	v_cvt_pk_bf16_f32 v155, v16, v17
	ds_read_u8 v16, v241
	ds_read_u8 v17, v241 offset:48
	ds_read_u8 v18, v241 offset:96
	ds_read_u8 v19, v241 offset:144
	ds_read_u8 v20, v241 offset:384
	ds_read_u8 v21, v241 offset:432
	ds_read_u8 v22, v241 offset:480
	ds_read_u8 v23, v241 offset:528
	s_waitcnt lgkmcnt(7)
	v_cvt_f32_ubyte0_e32 v16, v16
	v_mul_f32_e32 v16, 0x3b808081, v16
	s_waitcnt lgkmcnt(6)
	v_cvt_f32_ubyte0_e32 v17, v17
	v_lshlrev_b32_e32 v32, 16, v154
	v_mul_f32_e32 v17, 0x3b808081, v17
	v_fmac_f32_e32 v32, v16, v0
	v_and_b32_e32 v0, 0xffff0000, v154
	s_waitcnt lgkmcnt(5)
	v_cvt_f32_ubyte0_e32 v18, v18
	s_waitcnt lgkmcnt(4)
	v_cvt_f32_ubyte0_e32 v19, v19
	v_fmac_f32_e32 v0, v17, v1
	v_mul_f32_e32 v18, 0x3b808081, v18
	v_mul_f32_e32 v19, 0x3b808081, v19
	v_cvt_pk_bf16_f32 v154, v32, v0
	v_lshlrev_b32_e32 v0, 16, v153
	v_and_b32_e32 v1, 0xffff0000, v153
	s_waitcnt lgkmcnt(3)
	v_cvt_f32_ubyte0_e32 v20, v20
	s_waitcnt lgkmcnt(2)
	v_cvt_f32_ubyte0_e32 v21, v21
	v_fmac_f32_e32 v0, v18, v2
	v_fmac_f32_e32 v1, v19, v3
	v_mul_f32_e32 v20, 0x3b808081, v20
	v_mul_f32_e32 v21, 0x3b808081, v21
	v_cvt_pk_bf16_f32 v153, v0, v1
	v_lshlrev_b32_e32 v0, 16, v152
	v_and_b32_e32 v1, 0xffff0000, v152
	s_waitcnt lgkmcnt(1)
	v_cvt_f32_ubyte0_e32 v22, v22
	s_waitcnt lgkmcnt(0)
	v_cvt_f32_ubyte0_e32 v23, v23
	v_fmac_f32_e32 v0, v20, v4
	v_fmac_f32_e32 v1, v21, v5
	v_mul_f32_e32 v22, 0x3b808081, v22
	v_mul_f32_e32 v23, 0x3b808081, v23
	ds_read_u8 v24, v241 offset:768
	ds_read_u8 v25, v241 offset:816
	ds_read_u8 v26, v241 offset:864
	ds_read_u8 v27, v241 offset:912
	ds_read_u8 v28, v241 offset:1152
	ds_read_u8 v29, v241 offset:1200
	ds_read_u8 v30, v241 offset:1248
	ds_read_u8 v31, v241 offset:1296
	v_cvt_pk_bf16_f32 v152, v0, v1
	v_lshlrev_b32_e32 v0, 16, v145
	v_and_b32_e32 v1, 0xffff0000, v145
	s_waitcnt lgkmcnt(7)
	v_cvt_f32_ubyte0_e32 v24, v24
	s_waitcnt lgkmcnt(6)
	v_cvt_f32_ubyte0_e32 v25, v25
	v_fmac_f32_e32 v0, v22, v6
	v_fmac_f32_e32 v1, v23, v7
	v_mul_f32_e32 v24, 0x3b808081, v24
	v_mul_f32_e32 v25, 0x3b808081, v25
	v_cvt_pk_bf16_f32 v145, v0, v1
	v_lshlrev_b32_e32 v0, 16, v144
	v_and_b32_e32 v1, 0xffff0000, v144
	s_waitcnt lgkmcnt(5)
	v_cvt_f32_ubyte0_e32 v26, v26
	s_waitcnt lgkmcnt(4)
	v_cvt_f32_ubyte0_e32 v27, v27
	v_fmac_f32_e32 v0, v24, v8
	v_fmac_f32_e32 v1, v25, v9
	v_mul_f32_e32 v26, 0x3b808081, v26
	v_mul_f32_e32 v27, 0x3b808081, v27
	v_cvt_pk_bf16_f32 v144, v0, v1
	v_lshlrev_b32_e32 v0, 16, v143
	v_and_b32_e32 v1, 0xffff0000, v143
	s_waitcnt lgkmcnt(3)
	v_cvt_f32_ubyte0_e32 v28, v28
	s_waitcnt lgkmcnt(2)
	v_cvt_f32_ubyte0_e32 v29, v29
	v_fmac_f32_e32 v0, v26, v10
	v_fmac_f32_e32 v1, v27, v11
	v_mul_f32_e32 v28, 0x3b808081, v28
	v_mul_f32_e32 v29, 0x3b808081, v29
	v_cvt_pk_bf16_f32 v143, v0, v1
	v_lshlrev_b32_e32 v0, 16, v142
	v_and_b32_e32 v1, 0xffff0000, v142
	s_waitcnt lgkmcnt(1)
	v_cvt_f32_ubyte0_e32 v30, v30
	s_waitcnt lgkmcnt(0)
	v_cvt_f32_ubyte0_e32 v31, v31
	v_fmac_f32_e32 v0, v28, v12
	v_fmac_f32_e32 v1, v29, v13
	v_mul_f32_e32 v30, 0x3b808081, v30
	v_mul_f32_e32 v31, 0x3b808081, v31
	v_cvt_pk_bf16_f32 v142, v0, v1
	v_lshlrev_b32_e32 v0, 16, v141
	v_and_b32_e32 v1, 0xffff0000, v141
	v_fmac_f32_e32 v0, v30, v14
	v_fmac_f32_e32 v1, v31, v15
	v_cvt_pk_bf16_f32 v141, v0, v1
	v_mov_b32_e32 v0, 0
	v_mov_b32_e32 v1, v0
	v_mov_b32_e32 v2, v0
	v_mov_b32_e32 v3, v0
	v_mov_b32_e32 v4, v0
	v_mov_b32_e32 v5, v0
	v_mov_b32_e32 v6, v0
	v_mov_b32_e32 v7, v0
	v_mov_b32_e32 v8, v0
	v_mov_b32_e32 v9, v0
	v_mov_b32_e32 v10, v0
	v_mov_b32_e32 v11, v0
	v_mov_b32_e32 v12, v0
	v_mov_b32_e32 v13, v0
	v_mov_b32_e32 v14, v0
	v_mov_b32_e32 v15, v0
	v_mov_b32_e32 v16, v0
	v_mov_b32_e32 v17, v0
	v_mov_b32_e32 v18, v0
	v_mov_b32_e32 v19, v0
	v_mov_b32_e32 v20, v0
	v_mov_b32_e32 v21, v0
	v_mov_b32_e32 v22, v0
	v_mov_b32_e32 v23, v0
	v_mov_b32_e32 v24, v0
	v_mov_b32_e32 v25, v0
	v_mov_b32_e32 v26, v0
	v_mov_b32_e32 v27, v0
	v_mov_b32_e32 v28, v0
	v_mov_b32_e32 v29, v0
	v_mov_b32_e32 v30, v0
	v_mov_b32_e32 v31, v0
	v_mov_b32_e32 v32, v0
	v_mov_b32_e32 v33, v0
	v_mov_b32_e32 v34, v0
	v_mov_b32_e32 v35, v0
	v_mov_b32_e32 v36, v0
	v_mov_b32_e32 v37, v0
	v_mov_b32_e32 v38, v0
	v_mov_b32_e32 v39, v0
	v_mov_b32_e32 v40, v0
	v_mov_b32_e32 v41, v0
	v_mov_b32_e32 v42, v0
	v_mov_b32_e32 v43, v0
	v_mov_b32_e32 v44, v0
	v_mov_b32_e32 v45, v0
	v_mov_b32_e32 v46, v0
	v_mov_b32_e32 v47, v0
	v_mov_b32_e32 v48, v0
	v_mov_b32_e32 v49, v0
	v_mov_b32_e32 v50, v0
	v_mov_b32_e32 v51, v0
	v_mov_b32_e32 v52, v0
	v_mov_b32_e32 v53, v0
	v_mov_b32_e32 v54, v0
	v_mov_b32_e32 v55, v0
	v_mov_b32_e32 v56, v0
	v_mov_b32_e32 v57, v0
	v_mov_b32_e32 v58, v0
	v_mov_b32_e32 v59, v0
	v_mov_b32_e32 v60, v0
	v_mov_b32_e32 v61, v0
	v_mov_b32_e32 v62, v0
	v_mov_b32_e32 v63, v0
	s_branch .LBB0_1091

; #define INP(k) ({ int k_ = (k); LAUNDER_S(k_); (const float*)(const GAS float*)P.in[k_]; })
;     __host__ __device__ bool next(int i, Unit& u) const {
;         const long L = (long)i * G + c; if (L >= nwg) return false;
;         int wgid = (int)L; { const int q = nwg / NXCD, r = nwg % NXCD, xcd = wgid % NXCD, off = wgid / NXCD; wgid = (xcd < r ? xcd * (q + 1) : r * (q + 1) + (xcd - r) * q) + off; }
;         const int nig = WGM * nN, gid = wgid / nig, fm = gid * WGM, gsz = (nM - fm) < WGM ? (nM - fm) : WGM;
;         u.pm = fm + ((wgid % nig) % gsz); u.pn = (wgid % nig) / gsz; return true;
; __global__ void __launch_bounds__(512, 2) hybrid_fwd(Params P) {
;     ...
;         { PHASE_BEGIN
;             pg8::Gemm g{(const bf16_t*)(ws + WS_B), (const bf16_t*)(ws + WS_WOUT), MTOK, DM, DM, DM, DM}; pg8::StaticOrder S; S.init(MTOK, DM, G, bx);
;             if (L == 0) { EpiResNormB E{INP(0), (bf16_t*)(ws + WS_H), (float*)(ws + WS_SMALL + 262144)};
;                 pg8::gemm_phase<EpiResNormB, pg8::StaticOrder, true, true>(lds, g, S, E, tid); }
;             else { EpiResNormBB E{(const bf16_t*)POUT, (bf16_t*)(ws + WS_H), (float*)(ws + WS_SMALL + 262144)};
;                 pg8::gemm_phase<EpiResNormBB, pg8::StaticOrder, true, true>(lds, g, S, E, tid); }
.LBB0_1106:
	s_nop 0
	s_nop 0
	s_nop 0
	s_nop 0
	s_nop 0
	s_nop 0
	s_nop 0
	s_nop 0
	s_nop 0
	s_or_b64 exec, exec, s[4:5]
	s_mov_b32 s4, s34
	s_mov_b64 s[6:7], s[58:59]
	s_barrier
	s_add_u32 s38, s6, 0x13100000
	s_addc_u32 s39, s7, 0
	s_add_u32 s40, s6, 0xf00000
	s_addc_u32 s41, s7, 0
	s_mov_b32 s36, s69
	s_mov_b32 s37, s2
	v_mov_b32_e32 v140, v146
	s_cmp_lg_u32 s4, 0
	s_cbranch_scc0 .LBB0_1148
	s_cmpk_lt_i32 s37, 0x200
	s_cselect_b64 s[4:5], -1, 0
	s_cmpk_gt_i32 s37, 0x1ff
	v_readfirstlane_b32 s14, v140
	s_cbranch_scc1 .LBB0_1113
	s_ashr_i32 s8, s37, 31
	s_lshr_b32 s8, s8, 29
	s_add_i32 s10, s37, s8
	s_and_b32 s8, s10, -8
	s_sub_i32 s11, s37, s8
	s_cmp_gt_i32 s11, -1
	s_mov_b64 s[8:9], -1
	s_cbranch_scc0 .LBB0_1110
	s_lshl_b32 s12, s11, 6
	s_mov_b64 s[8:9], 0
